# v37 + runtime fallback to the original flat barrier when gridDim != 256 (XCC population assumption)
# baseline (speedup 1.0000x reference)
; #define SYNC(k) if (p.ph_lo <= (k) && (k) + 1 < p.ph_hi) { if ((k) == 0) grid.sync(); else gbar(bctr, bgen, gridDim.x); }
; DI void gbar(unsigned* ctr, unsigned& gen, unsigned G) {
;     asm volatile("s_waitcnt vmcnt(0)" ::: "memory");
;     __syncthreads();
;     gen += 1;
;     if (threadIdx.x == 0) {
;         __builtin_amdgcn_fence(__ATOMIC_RELEASE, "agent");
;         asm volatile("s_waitcnt vmcnt(0)" ::: "memory");
;         __hip_atomic_fetch_add(ctr, 1u, __ATOMIC_RELAXED, __HIP_MEMORY_SCOPE_AGENT);
;         while (__hip_atomic_load(ctr, __ATOMIC_RELAXED, __HIP_MEMORY_SCOPE_AGENT) < gen * G) __builtin_amdgcn_s_sleep(32);
;         __builtin_amdgcn_fence(__ATOMIC_ACQUIRE, "agent");
;         asm volatile("s_waitcnt vmcnt(0)" ::: "memory");
;     }
;     __syncthreads();
; }
; __global__ void __launch_bounds__(NTHREADS) fwd_megakernel(Params p) {
;     ...
;     SYNC(1)
.LBB0_1197:
	s_or_b64 exec, exec, s[18:19]
	v_cmp_gt_i32_e32 vcc, 2, v1
	v_cmp_lt_i32_e64 s[2:3], 2, v2
	s_and_b64 s[0:1], vcc, s[2:3]
	v_mov_b32_e32 v210, 0
	s_and_saveexec_b64 s[2:3], s[0:1]
	s_cbranch_execz .LBB0_1205
	s_waitcnt vmcnt(0)
	s_waitcnt lgkmcnt(0)
	v_and_b32_e32 v3, 0x3ff, v0
	v_cmp_eq_u32_e32 vcc, 0, v3
	s_waitcnt vmcnt(0)
	s_barrier
	s_and_saveexec_b64 s[4:5], vcc
	s_cbranch_execz .LBB0_1204
	s_cmp_lg_u32 s86, 0x100
	s_cbranch_scc1 .Lxb_flat_0
	s_getreg_b32 s1, hwreg(HW_REG_XCC_ID, 0, 4)
	s_lshl_b32 s1, s1, 8
	s_add_u32 s12, s42, 0x600000
	s_addc_u32 s13, s43, 0
	s_add_u32 s12, s12, s1
	s_addc_u32 s13, s13, 0
	s_add_u32 s14, s42, 0x601000
	s_addc_u32 s15, s43, 0
	s_lshr_b32 s16, s86, 3
	v_mov_b32_e32 v2, 0
	v_mov_b32_e32 v3, 1
	v_mov_b32_e32 v7, 1
	global_atomic_add v4, v2, v3, s[12:13] sc0
	v_mul_lo_u32 v8, v7, s16
	s_mov_b32 s0, 0
	s_waitcnt vmcnt(0)
	v_add_u32_e32 v4, 1, v4
	v_cmp_eq_u32_e32 vcc, v4, v8
	s_cbranch_vccz .Lxb_nl_0
	buffer_wbl2 sc1
	s_waitcnt vmcnt(0)
	global_atomic_add v4, v2, v3, s[14:15] sc0
	v_lshlrev_b32_e32 v8, 3, v7
	s_waitcnt vmcnt(0)
	v_add_u32_e32 v4, 1, v4
	v_cmp_eq_u32_e32 vcc, v4, v8
	s_cbranch_vccz .Lxb_wt_0
	global_atomic_add v2, v3, s[14:15] offset:256
	s_branch .Lxb_lr_0

; #define SYNC(k) if (p.ph_lo <= (k) && (k) + 1 < p.ph_hi) { if ((k) == 0) grid.sync(); else gbar(bctr, bgen, gridDim.x); }
; DI void gbar(unsigned* ctr, unsigned& gen, unsigned G) {
;     asm volatile("s_waitcnt vmcnt(0)" ::: "memory");
;     __syncthreads();
;     gen += 1;
;     if (threadIdx.x == 0) {
;         __builtin_amdgcn_fence(__ATOMIC_RELEASE, "agent");
;         asm volatile("s_waitcnt vmcnt(0)" ::: "memory");
;         __hip_atomic_fetch_add(ctr, 1u, __ATOMIC_RELAXED, __HIP_MEMORY_SCOPE_AGENT);
;         while (__hip_atomic_load(ctr, __ATOMIC_RELAXED, __HIP_MEMORY_SCOPE_AGENT) < gen * G) __builtin_amdgcn_s_sleep(32);
; __global__ void __launch_bounds__(NTHREADS) fwd_megakernel(Params p) {
;     ...
;     SYNC(1)
.Lxb_na_0:
	buffer_inv sc1
	s_waitcnt vmcnt(0)
.Lxb_dn_0:
	s_branch .Lxb_end_0
.Lxb_flat_0:
	s_mov_b64 s[6:7], exec
	buffer_wbl2 sc1
	s_waitcnt vmcnt(0)
	v_mbcnt_lo_u32_b32 v1, s6, 0
	v_mbcnt_hi_u32_b32 v1, s7, v1
	v_cmp_eq_u32_e32 vcc, 0, v1
	s_and_saveexec_b64 s[8:9], vcc
	s_cbranch_execz .LBB0_1201
	s_bcnt1_i32_b64 s0, s[6:7]
	v_mov_b32_e32 v1, 0
	v_mov_b32_e32 v2, s0
	global_atomic_add v1, v2, s[62:63]

; #define SYNC(k) if (p.ph_lo <= (k) && (k) + 1 < p.ph_hi) { if ((k) == 0) grid.sync(); else gbar(bctr, bgen, gridDim.x); }
; DI void gbar(unsigned* ctr, unsigned& gen, unsigned G) {
;     asm volatile("s_waitcnt vmcnt(0)" ::: "memory");
;     __syncthreads();
;     gen += 1;
;     if (threadIdx.x == 0) {
;         __builtin_amdgcn_fence(__ATOMIC_RELEASE, "agent");
;         asm volatile("s_waitcnt vmcnt(0)" ::: "memory");
;         __hip_atomic_fetch_add(ctr, 1u, __ATOMIC_RELAXED, __HIP_MEMORY_SCOPE_AGENT);
;         while (__hip_atomic_load(ctr, __ATOMIC_RELAXED, __HIP_MEMORY_SCOPE_AGENT) < gen * G) __builtin_amdgcn_s_sleep(32);
;         __builtin_amdgcn_fence(__ATOMIC_ACQUIRE, "agent");
;         asm volatile("s_waitcnt vmcnt(0)" ::: "memory");
;     }
;     __syncthreads();
; }
; __global__ void __launch_bounds__(NTHREADS) fwd_megakernel(Params p) {
;     ...
;     SYNC(2)
.LBB0_1236:
	s_or_b64 exec, exec, s[22:23]
	s_cmp_lt_i32 s90, 3
	s_cselect_b64 s[0:1], -1, 0
	s_cmp_gt_i32 s91, 3
	s_cselect_b64 s[2:3], -1, 0
	s_and_b64 s[0:1], s[0:1], s[2:3]
	s_andn2_b64 vcc, exec, s[0:1]
	s_cbranch_vccnz .LBB0_1245
	s_waitcnt vmcnt(0)
	v_and_b32_e32 v1, 0x3ff, v0
	v_add_u32_e32 v210, 1, v210
	v_cmp_eq_u32_e32 vcc, 0, v1
	v_mov_b32_e32 v1, s90
	s_waitcnt lgkmcnt(0)
	v_mov_b32_e32 v5, s91
	s_waitcnt vmcnt(0)
	s_barrier
	s_and_saveexec_b64 s[2:3], vcc
	s_cbranch_execz .LBB0_1244
	s_cmp_lg_u32 s86, 0x100
	s_cbranch_scc1 .Lxb_flat_1
	s_getreg_b32 s1, hwreg(HW_REG_XCC_ID, 0, 4)
	s_lshl_b32 s1, s1, 8
	s_add_u32 s12, s42, 0x600000
	s_addc_u32 s13, s43, 0
	s_add_u32 s12, s12, s1
	s_addc_u32 s13, s13, 0
	s_add_u32 s14, s42, 0x601000
	s_addc_u32 s15, s43, 0
	s_lshr_b32 s16, s86, 3
	v_mov_b32_e32 v2, 0
	v_mov_b32_e32 v3, 1
	v_mov_b32_e32 v7, v210
	global_atomic_add v4, v2, v3, s[12:13] sc0
	v_mul_lo_u32 v8, v7, s16
	s_mov_b32 s0, 0
	s_waitcnt vmcnt(0)
	v_add_u32_e32 v4, 1, v4
	v_cmp_eq_u32_e32 vcc, v4, v8
	s_cbranch_vccz .Lxb_nl_1
	buffer_wbl2 sc1
	s_waitcnt vmcnt(0)
	global_atomic_add v4, v2, v3, s[14:15] sc0
	v_lshlrev_b32_e32 v8, 3, v7
	s_waitcnt vmcnt(0)
	v_add_u32_e32 v4, 1, v4
	v_cmp_eq_u32_e32 vcc, v4, v8
	s_cbranch_vccz .Lxb_wt_1
	global_atomic_add v2, v3, s[14:15] offset:256
	s_branch .Lxb_lr_1

; #define SYNC(k) if (p.ph_lo <= (k) && (k) + 1 < p.ph_hi) { if ((k) == 0) grid.sync(); else gbar(bctr, bgen, gridDim.x); }
; DI void gbar(unsigned* ctr, unsigned& gen, unsigned G) {
;     asm volatile("s_waitcnt vmcnt(0)" ::: "memory");
;     __syncthreads();
;     gen += 1;
;     if (threadIdx.x == 0) {
;         __builtin_amdgcn_fence(__ATOMIC_RELEASE, "agent");
;         asm volatile("s_waitcnt vmcnt(0)" ::: "memory");
;         __hip_atomic_fetch_add(ctr, 1u, __ATOMIC_RELAXED, __HIP_MEMORY_SCOPE_AGENT);
;         while (__hip_atomic_load(ctr, __ATOMIC_RELAXED, __HIP_MEMORY_SCOPE_AGENT) < gen * G) __builtin_amdgcn_s_sleep(32);
; __global__ void __launch_bounds__(NTHREADS) fwd_megakernel(Params p) {
;     ...
;     SYNC(2)
.Lxb_na_1:
	buffer_inv sc1
	s_waitcnt vmcnt(0)
.Lxb_dn_1:
	s_branch .Lxb_end_1
.Lxb_flat_1:
	s_mov_b64 s[4:5], exec
	buffer_wbl2 sc1
	s_waitcnt vmcnt(0)
	v_mbcnt_lo_u32_b32 v1, s4, 0
	v_mbcnt_hi_u32_b32 v1, s5, v1
	v_cmp_eq_u32_e32 vcc, 0, v1
	s_and_saveexec_b64 s[6:7], vcc
	s_cbranch_execz .LBB0_1240
	s_bcnt1_i32_b64 s0, s[4:5]
	v_mov_b32_e32 v1, 0
	v_mov_b32_e32 v2, s0
	global_atomic_add v1, v2, s[62:63]

; DI void gbar(unsigned* ctr, unsigned& gen, unsigned G) {
;     ...
;         __builtin_amdgcn_fence(__ATOMIC_ACQUIRE, "agent");
;         asm volatile("s_waitcnt vmcnt(0)" ::: "memory");
.LBB0_1243:
	s_or_b64 exec, exec, s[4:5]
	buffer_inv sc1
	s_waitcnt vmcnt(0)

; #define SYNC(k) if (p.ph_lo <= (k) && (k) + 1 < p.ph_hi) { if ((k) == 0) grid.sync(); else gbar(bctr, bgen, gridDim.x); }
; DI void gbar(unsigned* ctr, unsigned& gen, unsigned G) {
;     asm volatile("s_waitcnt vmcnt(0)" ::: "memory");
;     __syncthreads();
;     gen += 1;
;     if (threadIdx.x == 0) {
;         __builtin_amdgcn_fence(__ATOMIC_RELEASE, "agent");
;         asm volatile("s_waitcnt vmcnt(0)" ::: "memory");
;         __hip_atomic_fetch_add(ctr, 1u, __ATOMIC_RELAXED, __HIP_MEMORY_SCOPE_AGENT);
;         while (__hip_atomic_load(ctr, __ATOMIC_RELAXED, __HIP_MEMORY_SCOPE_AGENT) < gen * G) __builtin_amdgcn_s_sleep(32);
;         __builtin_amdgcn_fence(__ATOMIC_ACQUIRE, "agent");
;         asm volatile("s_waitcnt vmcnt(0)" ::: "memory");
;     }
;     __syncthreads();
; }
; __global__ void __launch_bounds__(NTHREADS) fwd_megakernel(Params p) {
;     ...
;     SYNC(3)
.LBB0_1391:
	s_or_b64 exec, exec, s[72:73]
	v_cmp_gt_i32_e32 vcc, 4, v1
	v_cmp_lt_i32_e64 s[2:3], 4, v5
	s_and_b64 s[0:1], vcc, s[2:3]
	s_and_saveexec_b64 s[2:3], s[0:1]
	s_cbranch_execz .LBB0_1400
	s_waitcnt vmcnt(0)
	v_and_b32_e32 v2, 0x3ff, v0
	v_add_u32_e32 v210, 1, v210
	v_cmp_eq_u32_e32 vcc, 0, v2
	s_waitcnt vmcnt(0)
	s_barrier
	s_and_saveexec_b64 s[4:5], vcc
	s_cbranch_execz .LBB0_1399
	s_cmp_lg_u32 s86, 0x100
	s_cbranch_scc1 .Lxb_flat_2
	s_getreg_b32 s1, hwreg(HW_REG_XCC_ID, 0, 4)
	s_lshl_b32 s1, s1, 8
	s_add_u32 s12, s42, 0x600000
	s_addc_u32 s13, s43, 0
	s_add_u32 s12, s12, s1
	s_addc_u32 s13, s13, 0
	s_add_u32 s14, s42, 0x601000
	s_addc_u32 s15, s43, 0
	s_lshr_b32 s16, s86, 3
	v_mov_b32_e32 v2, 0
	v_mov_b32_e32 v3, 1
	v_mov_b32_e32 v7, v210
	global_atomic_add v4, v2, v3, s[12:13] sc0
	v_mul_lo_u32 v8, v7, s16
	s_mov_b32 s0, 0
	s_waitcnt vmcnt(0)
	v_add_u32_e32 v4, 1, v4
	v_cmp_eq_u32_e32 vcc, v4, v8
	s_cbranch_vccz .Lxb_nl_2
	buffer_wbl2 sc1
	s_waitcnt vmcnt(0)
	global_atomic_add v4, v2, v3, s[14:15] sc0
	v_lshlrev_b32_e32 v8, 3, v7
	s_waitcnt vmcnt(0)
	v_add_u32_e32 v4, 1, v4
	v_cmp_eq_u32_e32 vcc, v4, v8
	s_cbranch_vccz .Lxb_wt_2
	global_atomic_add v2, v3, s[14:15] offset:256
	s_branch .Lxb_lr_2

; #define SYNC(k) if (p.ph_lo <= (k) && (k) + 1 < p.ph_hi) { if ((k) == 0) grid.sync(); else gbar(bctr, bgen, gridDim.x); }
; DI void gbar(unsigned* ctr, unsigned& gen, unsigned G) {
;     ...
;         asm volatile("s_waitcnt vmcnt(0)" ::: "memory");
;     }
;     __syncthreads();
; __global__ void __launch_bounds__(NTHREADS) fwd_megakernel(Params p) {
;     ...
;     SYNC(3)
.Lxb_na_2:
	buffer_inv sc1
	s_waitcnt vmcnt(0)
.Lxb_dn_2:
	s_branch .Lxb_end_2

; DI void gbar(unsigned* ctr, unsigned& gen, unsigned G) {
;     ...
;         __builtin_amdgcn_fence(__ATOMIC_ACQUIRE, "agent");
;         asm volatile("s_waitcnt vmcnt(0)" ::: "memory");
.LBB0_1398:
	s_or_b64 exec, exec, s[6:7]
	buffer_inv sc1
	s_waitcnt vmcnt(0)

; #define SYNC(k) if (p.ph_lo <= (k) && (k) + 1 < p.ph_hi) { if ((k) == 0) grid.sync(); else gbar(bctr, bgen, gridDim.x); }
; DI void gbar(unsigned* ctr, unsigned& gen, unsigned G) {
;     asm volatile("s_waitcnt vmcnt(0)" ::: "memory");
;     __syncthreads();
;     gen += 1;
;     if (threadIdx.x == 0) {
;         __builtin_amdgcn_fence(__ATOMIC_RELEASE, "agent");
;         asm volatile("s_waitcnt vmcnt(0)" ::: "memory");
;         __hip_atomic_fetch_add(ctr, 1u, __ATOMIC_RELAXED, __HIP_MEMORY_SCOPE_AGENT);
;         while (__hip_atomic_load(ctr, __ATOMIC_RELAXED, __HIP_MEMORY_SCOPE_AGENT) < gen * G) __builtin_amdgcn_s_sleep(32);
;         __builtin_amdgcn_fence(__ATOMIC_ACQUIRE, "agent");
;         asm volatile("s_waitcnt vmcnt(0)" ::: "memory");
;     }
;     __syncthreads();
; }
; __global__ void __launch_bounds__(NTHREADS) fwd_megakernel(Params p) {
;     ...
;     SYNC(4)
.LBB0_1445:
	s_or_b64 exec, exec, s[6:7]
	v_cmp_gt_i32_e32 vcc, 5, v1
	v_cmp_lt_i32_e64 s[2:3], 5, v5
	s_and_b64 s[0:1], vcc, s[2:3]
	s_and_saveexec_b64 s[2:3], s[0:1]
	s_cbranch_execz .LBB0_1454
	s_waitcnt vmcnt(0)
	v_and_b32_e32 v2, 0x3ff, v0
	v_add_u32_e32 v210, 1, v210
	v_cmp_eq_u32_e32 vcc, 0, v2
	s_waitcnt vmcnt(0) lgkmcnt(0)
	s_barrier
	s_and_saveexec_b64 s[4:5], vcc
	s_cbranch_execz .LBB0_1453
	s_cmp_lg_u32 s86, 0x100
	s_cbranch_scc1 .Lxb_flat_3
	s_getreg_b32 s1, hwreg(HW_REG_XCC_ID, 0, 4)
	s_lshl_b32 s1, s1, 8
	s_add_u32 s12, s42, 0x600000
	s_addc_u32 s13, s43, 0
	s_add_u32 s12, s12, s1
	s_addc_u32 s13, s13, 0
	s_add_u32 s14, s42, 0x601000
	s_addc_u32 s15, s43, 0
	s_lshr_b32 s16, s86, 3
	v_mov_b32_e32 v2, 0
	v_mov_b32_e32 v3, 1
	v_mov_b32_e32 v7, v210
	global_atomic_add v4, v2, v3, s[12:13] sc0
	v_mul_lo_u32 v8, v7, s16
	s_mov_b32 s0, 0
	s_waitcnt vmcnt(0)
	v_add_u32_e32 v4, 1, v4
	v_cmp_eq_u32_e32 vcc, v4, v8
	s_cbranch_vccz .Lxb_nl_3
	buffer_wbl2 sc1
	s_waitcnt vmcnt(0)
	global_atomic_add v4, v2, v3, s[14:15] sc0
	v_lshlrev_b32_e32 v8, 3, v7
	s_waitcnt vmcnt(0)
	v_add_u32_e32 v4, 1, v4
	v_cmp_eq_u32_e32 vcc, v4, v8
	s_cbranch_vccz .Lxb_wt_3
	global_atomic_add v2, v3, s[14:15] offset:256
	s_branch .Lxb_lr_3

; #define SYNC(k) if (p.ph_lo <= (k) && (k) + 1 < p.ph_hi) { if ((k) == 0) grid.sync(); else gbar(bctr, bgen, gridDim.x); }
; DI void gbar(unsigned* ctr, unsigned& gen, unsigned G) {
;     ...
;         asm volatile("s_waitcnt vmcnt(0)" ::: "memory");
;     }
;     __syncthreads();
; __global__ void __launch_bounds__(NTHREADS) fwd_megakernel(Params p) {
;     ...
;     SYNC(4)
.Lxb_na_3:
	buffer_inv sc1
	s_waitcnt vmcnt(0)
.Lxb_dn_3:
	s_branch .Lxb_end_3

; #define SYNC(k) if (p.ph_lo <= (k) && (k) + 1 < p.ph_hi) { if ((k) == 0) grid.sync(); else gbar(bctr, bgen, gridDim.x); }
; DI void gbar(unsigned* ctr, unsigned& gen, unsigned G) {
;     asm volatile("s_waitcnt vmcnt(0)" ::: "memory");
;     __syncthreads();
;     gen += 1;
;     if (threadIdx.x == 0) {
;         __builtin_amdgcn_fence(__ATOMIC_RELEASE, "agent");
;         asm volatile("s_waitcnt vmcnt(0)" ::: "memory");
;         __hip_atomic_fetch_add(ctr, 1u, __ATOMIC_RELAXED, __HIP_MEMORY_SCOPE_AGENT);
;         while (__hip_atomic_load(ctr, __ATOMIC_RELAXED, __HIP_MEMORY_SCOPE_AGENT) < gen * G) __builtin_amdgcn_s_sleep(32);
;         __builtin_amdgcn_fence(__ATOMIC_ACQUIRE, "agent");
;         asm volatile("s_waitcnt vmcnt(0)" ::: "memory");
;     }
;     __syncthreads();
; }
; __global__ void __launch_bounds__(NTHREADS) fwd_megakernel(Params p) {
;     ...
;     SYNC(5)
.LBB0_1479:
	s_or_b64 exec, exec, s[4:5]
	v_cmp_gt_i32_e32 vcc, 6, v1
	v_cmp_lt_i32_e64 s[2:3], 6, v5
	s_and_b64 s[0:1], vcc, s[2:3]
	s_and_saveexec_b64 s[2:3], s[0:1]
	s_cbranch_execz .LBB0_1488
	s_waitcnt vmcnt(0)
	v_and_b32_e32 v2, 0x3ff, v0
	v_add_u32_e32 v210, 1, v210
	v_cmp_eq_u32_e32 vcc, 0, v2
	s_waitcnt vmcnt(0) lgkmcnt(0)
	s_barrier
	s_and_saveexec_b64 s[4:5], vcc
	s_cbranch_execz .LBB0_1487
	s_cmp_lg_u32 s86, 0x100
	s_cbranch_scc1 .Lxb_flat_4
	s_getreg_b32 s1, hwreg(HW_REG_XCC_ID, 0, 4)
	s_lshl_b32 s1, s1, 8
	s_add_u32 s12, s42, 0x600000
	s_addc_u32 s13, s43, 0
	s_add_u32 s12, s12, s1
	s_addc_u32 s13, s13, 0
	s_add_u32 s14, s42, 0x601000
	s_addc_u32 s15, s43, 0
	s_lshr_b32 s16, s86, 3
	v_mov_b32_e32 v2, 0
	v_mov_b32_e32 v3, 1
	v_mov_b32_e32 v7, v210
	global_atomic_add v4, v2, v3, s[12:13] sc0
	v_mul_lo_u32 v8, v7, s16
	s_mov_b32 s0, 0
	s_waitcnt vmcnt(0)
	v_add_u32_e32 v4, 1, v4
	v_cmp_eq_u32_e32 vcc, v4, v8
	s_cbranch_vccz .Lxb_nl_4
	buffer_wbl2 sc1
	s_waitcnt vmcnt(0)
	global_atomic_add v4, v2, v3, s[14:15] sc0
	v_lshlrev_b32_e32 v8, 3, v7
	s_waitcnt vmcnt(0)
	v_add_u32_e32 v4, 1, v4
	v_cmp_eq_u32_e32 vcc, v4, v8
	s_cbranch_vccz .Lxb_wt_4
	global_atomic_add v2, v3, s[14:15] offset:256
	s_branch .Lxb_lr_4

; #define SYNC(k) if (p.ph_lo <= (k) && (k) + 1 < p.ph_hi) { if ((k) == 0) grid.sync(); else gbar(bctr, bgen, gridDim.x); }
; DI void gbar(unsigned* ctr, unsigned& gen, unsigned G) {
;     ...
;         asm volatile("s_waitcnt vmcnt(0)" ::: "memory");
;     }
;     __syncthreads();
; __global__ void __launch_bounds__(NTHREADS) fwd_megakernel(Params p) {
;     ...
;     SYNC(5)
.Lxb_na_4:
	buffer_inv sc1
	s_waitcnt vmcnt(0)
.Lxb_dn_4:
	s_branch .Lxb_end_4

; #define PH(k) if (p.ph_lo <= (k) && (k) < p.ph_hi)
; #define GEMM(EPI, e, A_, W_, N_, K_) { pg8::Gemm g{A_, W_, T_TOK, N_, K_}; pg8::StaticOrder S; S.init(T_TOK, N_, (int)gridDim.x, (int)blockIdx.x); \
;         pg8::gemm_phase<EPI, pg8::StaticOrder, true, true>(l3, g, S, e); }
; DI void gbar(unsigned* ctr, unsigned& gen, unsigned G) {
;     asm volatile("s_waitcnt vmcnt(0)" ::: "memory");
;     __syncthreads();
;     gen += 1;
;     if (threadIdx.x == 0) {
;         __builtin_amdgcn_fence(__ATOMIC_RELEASE, "agent");
;         asm volatile("s_waitcnt vmcnt(0)" ::: "memory");
;         __hip_atomic_fetch_add(ctr, 1u, __ATOMIC_RELAXED, __HIP_MEMORY_SCOPE_AGENT);
;         while (__hip_atomic_load(ctr, __ATOMIC_RELAXED, __HIP_MEMORY_SCOPE_AGENT) < gen * G) __builtin_amdgcn_s_sleep(32);
;         __builtin_amdgcn_fence(__ATOMIC_ACQUIRE, "agent");
;         asm volatile("s_waitcnt vmcnt(0)" ::: "memory");
;     }
;     __syncthreads();
; }
; __global__ void __launch_bounds__(NTHREADS) fwd_megakernel(Params p) {
;     ...
;     PH(7) { EpiProj1b e{sumsq + 2 * T_TOK, pbuf, vt, (float*)(ws + WS_BITMASK), (float*)(ws + WS_IW), rope}; GEMM(EpiProj1b, e, hb, (const bf16_t*)(ws + WS_WT_IN1), 3840, 1024) }
.LBB0_1531:
	s_or_b64 exec, exec, s[6:7]
	v_cmp_gt_i32_e32 vcc, 7, v1
	v_cmp_lt_i32_e64 s[2:3], 7, v5
	s_and_b64 s[0:1], vcc, s[2:3]
	s_and_saveexec_b64 s[2:3], s[0:1]
	s_cbranch_execz .LBB0_1540
	s_waitcnt vmcnt(0)
	v_and_b32_e32 v2, 0x3ff, v0
	v_add_u32_e32 v210, 1, v210
	v_cmp_eq_u32_e32 vcc, 0, v2
	s_waitcnt vmcnt(0) lgkmcnt(0)
	s_barrier
	s_and_saveexec_b64 s[4:5], vcc
	s_cbranch_execz .LBB0_1539
	s_cmp_lg_u32 s86, 0x100
	s_cbranch_scc1 .Lxb_flat_5
	s_getreg_b32 s1, hwreg(HW_REG_XCC_ID, 0, 4)
	s_lshl_b32 s1, s1, 8
	s_add_u32 s12, s42, 0x600000
	s_addc_u32 s13, s43, 0
	s_add_u32 s12, s12, s1
	s_addc_u32 s13, s13, 0
	s_add_u32 s14, s42, 0x601000
	s_addc_u32 s15, s43, 0
	s_lshr_b32 s16, s86, 3
	v_mov_b32_e32 v2, 0
	v_mov_b32_e32 v3, 1
	v_mov_b32_e32 v7, v210
	global_atomic_add v4, v2, v3, s[12:13] sc0
	v_mul_lo_u32 v8, v7, s16
	s_mov_b32 s0, 0
	s_waitcnt vmcnt(0)
	v_add_u32_e32 v4, 1, v4
	v_cmp_eq_u32_e32 vcc, v4, v8
	s_cbranch_vccz .Lxb_nl_5
	buffer_wbl2 sc1
	s_waitcnt vmcnt(0)
	global_atomic_add v4, v2, v3, s[14:15] sc0
	v_lshlrev_b32_e32 v8, 3, v7
	s_waitcnt vmcnt(0)
	v_add_u32_e32 v4, 1, v4
	v_cmp_eq_u32_e32 vcc, v4, v8
	s_cbranch_vccz .Lxb_wt_5
	global_atomic_add v2, v3, s[14:15] offset:256
	s_branch .Lxb_lr_5

; #define PH(k) if (p.ph_lo <= (k) && (k) < p.ph_hi)
; #define GEMM(EPI, e, A_, W_, N_, K_) { pg8::Gemm g{A_, W_, T_TOK, N_, K_}; pg8::StaticOrder S; S.init(T_TOK, N_, (int)gridDim.x, (int)blockIdx.x); \
;         pg8::gemm_phase<EPI, pg8::StaticOrder, true, true>(l3, g, S, e); }
; DI void gbar(unsigned* ctr, unsigned& gen, unsigned G) {
;     ...
;         asm volatile("s_waitcnt vmcnt(0)" ::: "memory");
;     }
;     __syncthreads();
; __global__ void __launch_bounds__(NTHREADS) fwd_megakernel(Params p) {
;     ...
;     PH(7) { EpiProj1b e{sumsq + 2 * T_TOK, pbuf, vt, (float*)(ws + WS_BITMASK), (float*)(ws + WS_IW), rope}; GEMM(EpiProj1b, e, hb, (const bf16_t*)(ws + WS_WT_IN1), 3840, 1024) }
.Lxb_na_5:
	buffer_inv sc1
	s_waitcnt vmcnt(0)
.Lxb_dn_5:
	s_branch .Lxb_end_5

; #define SYNC(k) if (p.ph_lo <= (k) && (k) + 1 < p.ph_hi) { if ((k) == 0) grid.sync(); else gbar(bctr, bgen, gridDim.x); }
; DI void gbar(unsigned* ctr, unsigned& gen, unsigned G) {
;     asm volatile("s_waitcnt vmcnt(0)" ::: "memory");
;     __syncthreads();
;     gen += 1;
;     if (threadIdx.x == 0) {
;         __builtin_amdgcn_fence(__ATOMIC_RELEASE, "agent");
;         asm volatile("s_waitcnt vmcnt(0)" ::: "memory");
;         __hip_atomic_fetch_add(ctr, 1u, __ATOMIC_RELAXED, __HIP_MEMORY_SCOPE_AGENT);
;         while (__hip_atomic_load(ctr, __ATOMIC_RELAXED, __HIP_MEMORY_SCOPE_AGENT) < gen * G) __builtin_amdgcn_s_sleep(32);
;         __builtin_amdgcn_fence(__ATOMIC_ACQUIRE, "agent");
;         asm volatile("s_waitcnt vmcnt(0)" ::: "memory");
;     }
;     __syncthreads();
; }
; __global__ void __launch_bounds__(NTHREADS) fwd_megakernel(Params p) {
;     ...
;     SYNC(7)
.LBB0_2532:
	s_or_b64 exec, exec, s[12:13]
	v_cmp_gt_i32_e32 vcc, 8, v1
	v_cmp_lt_i32_e64 s[2:3], 8, v5
	s_and_b64 s[0:1], vcc, s[2:3]
	s_and_saveexec_b64 s[2:3], s[0:1]
	s_cbranch_execz .LBB0_2541
	s_waitcnt vmcnt(0)
	v_and_b32_e32 v2, 0x3ff, v0
	v_add_u32_e32 v210, 1, v210
	v_cmp_eq_u32_e32 vcc, 0, v2
	s_waitcnt vmcnt(0) lgkmcnt(0)
	s_barrier
	s_and_saveexec_b64 s[4:5], vcc
	s_cbranch_execz .LBB0_2540
	s_cmp_lg_u32 s86, 0x100
	s_cbranch_scc1 .Lxb_flat_6
	s_getreg_b32 s1, hwreg(HW_REG_XCC_ID, 0, 4)
	s_lshl_b32 s1, s1, 8
	s_add_u32 s12, s42, 0x600000
	s_addc_u32 s13, s43, 0
	s_add_u32 s12, s12, s1
	s_addc_u32 s13, s13, 0
	s_add_u32 s14, s42, 0x601000
	s_addc_u32 s15, s43, 0
	s_lshr_b32 s16, s86, 3
	v_mov_b32_e32 v2, 0
	v_mov_b32_e32 v3, 1
	v_mov_b32_e32 v7, v210
	global_atomic_add v4, v2, v3, s[12:13] sc0
	v_mul_lo_u32 v8, v7, s16
	s_mov_b32 s0, 0
	s_waitcnt vmcnt(0)
	v_add_u32_e32 v4, 1, v4
	v_cmp_eq_u32_e32 vcc, v4, v8
	s_cbranch_vccz .Lxb_nl_6
	buffer_wbl2 sc1
	s_waitcnt vmcnt(0)
	global_atomic_add v4, v2, v3, s[14:15] sc0
	v_lshlrev_b32_e32 v8, 3, v7
	s_waitcnt vmcnt(0)
	v_add_u32_e32 v4, 1, v4
	v_cmp_eq_u32_e32 vcc, v4, v8
	s_cbranch_vccz .Lxb_wt_6
	global_atomic_add v2, v3, s[14:15] offset:256
	s_branch .Lxb_lr_6

; #define SYNC(k) if (p.ph_lo <= (k) && (k) + 1 < p.ph_hi) { if ((k) == 0) grid.sync(); else gbar(bctr, bgen, gridDim.x); }
; DI void gbar(unsigned* ctr, unsigned& gen, unsigned G) {
;     ...
;         asm volatile("s_waitcnt vmcnt(0)" ::: "memory");
;     }
;     __syncthreads();
; __global__ void __launch_bounds__(NTHREADS) fwd_megakernel(Params p) {
;     ...
;     SYNC(7)
.Lxb_na_6:
	buffer_inv sc1
	s_waitcnt vmcnt(0)
.Lxb_dn_6:
	s_branch .Lxb_end_6

; #define SYNC(k) if (p.ph_lo <= (k) && (k) + 1 < p.ph_hi) { if ((k) == 0) grid.sync(); else gbar(bctr, bgen, gridDim.x); }
; DI void gbar(unsigned* ctr, unsigned& gen, unsigned G) {
;     asm volatile("s_waitcnt vmcnt(0)" ::: "memory");
;     __syncthreads();
;     gen += 1;
;     if (threadIdx.x == 0) {
;         __builtin_amdgcn_fence(__ATOMIC_RELEASE, "agent");
;         asm volatile("s_waitcnt vmcnt(0)" ::: "memory");
;         __hip_atomic_fetch_add(ctr, 1u, __ATOMIC_RELAXED, __HIP_MEMORY_SCOPE_AGENT);
;         while (__hip_atomic_load(ctr, __ATOMIC_RELAXED, __HIP_MEMORY_SCOPE_AGENT) < gen * G) __builtin_amdgcn_s_sleep(32);
;         __builtin_amdgcn_fence(__ATOMIC_ACQUIRE, "agent");
;         asm volatile("s_waitcnt vmcnt(0)" ::: "memory");
;     }
;     __syncthreads();
; }
; __global__ void __launch_bounds__(NTHREADS) fwd_megakernel(Params p) {
;     ...
;     SYNC(8)
.LBB0_2545:
	s_or_b64 exec, exec, s[8:9]
	v_cmp_lt_i32_e64 s[2:3], 9, v5
	s_and_b64 s[0:1], vcc, s[2:3]
	s_and_saveexec_b64 s[2:3], s[0:1]
	s_cbranch_execz .LBB0_2554
	s_waitcnt vmcnt(0)
	v_and_b32_e32 v2, 0x3ff, v0
	v_add_u32_e32 v210, 1, v210
	v_cmp_eq_u32_e32 vcc, 0, v2
	s_waitcnt vmcnt(0)
	s_barrier
	s_and_saveexec_b64 s[4:5], vcc
	s_cbranch_execz .LBB0_2553
	s_cmp_lg_u32 s86, 0x100
	s_cbranch_scc1 .Lxb_flat_7
	s_getreg_b32 s1, hwreg(HW_REG_XCC_ID, 0, 4)
	s_lshl_b32 s1, s1, 8
	s_add_u32 s12, s42, 0x600000
	s_addc_u32 s13, s43, 0
	s_add_u32 s12, s12, s1
	s_addc_u32 s13, s13, 0
	s_add_u32 s14, s42, 0x601000
	s_addc_u32 s15, s43, 0
	s_lshr_b32 s16, s86, 3
	v_mov_b32_e32 v2, 0
	v_mov_b32_e32 v3, 1
	v_mov_b32_e32 v7, v210
	global_atomic_add v4, v2, v3, s[12:13] sc0
	v_mul_lo_u32 v8, v7, s16
	s_mov_b32 s0, 0
	s_waitcnt vmcnt(0)
	v_add_u32_e32 v4, 1, v4
	v_cmp_eq_u32_e32 vcc, v4, v8
	s_cbranch_vccz .Lxb_nl_7
	buffer_wbl2 sc1
	s_waitcnt vmcnt(0)
	global_atomic_add v4, v2, v3, s[14:15] sc0
	v_lshlrev_b32_e32 v8, 3, v7
	s_waitcnt vmcnt(0)
	v_add_u32_e32 v4, 1, v4
	v_cmp_eq_u32_e32 vcc, v4, v8
	s_cbranch_vccz .Lxb_wt_7
	global_atomic_add v2, v3, s[14:15] offset:256
	s_branch .Lxb_lr_7

; #define SYNC(k) if (p.ph_lo <= (k) && (k) + 1 < p.ph_hi) { if ((k) == 0) grid.sync(); else gbar(bctr, bgen, gridDim.x); }
; DI void gbar(unsigned* ctr, unsigned& gen, unsigned G) {
;     ...
;         asm volatile("s_waitcnt vmcnt(0)" ::: "memory");
;     }
;     __syncthreads();
; __global__ void __launch_bounds__(NTHREADS) fwd_megakernel(Params p) {
;     ...
;     SYNC(8)
.Lxb_na_7:
	buffer_inv sc1
	s_waitcnt vmcnt(0)
.Lxb_dn_7:
	s_branch .Lxb_end_7

; #define SYNC(k) if (p.ph_lo <= (k) && (k) + 1 < p.ph_hi) { if ((k) == 0) grid.sync(); else gbar(bctr, bgen, gridDim.x); }
; DI void gbar(unsigned* ctr, unsigned& gen, unsigned G) {
;     asm volatile("s_waitcnt vmcnt(0)" ::: "memory");
;     __syncthreads();
;     gen += 1;
;     if (threadIdx.x == 0) {
;         __builtin_amdgcn_fence(__ATOMIC_RELEASE, "agent");
;         asm volatile("s_waitcnt vmcnt(0)" ::: "memory");
;         __hip_atomic_fetch_add(ctr, 1u, __ATOMIC_RELAXED, __HIP_MEMORY_SCOPE_AGENT);
;         while (__hip_atomic_load(ctr, __ATOMIC_RELAXED, __HIP_MEMORY_SCOPE_AGENT) < gen * G) __builtin_amdgcn_s_sleep(32);
;         __builtin_amdgcn_fence(__ATOMIC_ACQUIRE, "agent");
;         asm volatile("s_waitcnt vmcnt(0)" ::: "memory");
;     }
;     __syncthreads();
; }
; __global__ void __launch_bounds__(NTHREADS) fwd_megakernel(Params p) {
;     ...
;     SYNC(9)
.LBB0_3580:
	s_or_b64 exec, exec, s[2:3]
	v_cmp_gt_i32_e32 vcc, 10, v1
	v_cmp_lt_i32_e64 s[2:3], 10, v5
	s_and_b64 s[0:1], vcc, s[2:3]
	s_and_saveexec_b64 s[2:3], s[0:1]
	s_cbranch_execz .LBB0_3589
	s_waitcnt vmcnt(0)
	v_and_b32_e32 v2, 0x3ff, v0
	v_add_u32_e32 v210, 1, v210
	v_cmp_eq_u32_e32 vcc, 0, v2
	s_waitcnt vmcnt(0)
	s_barrier
	s_and_saveexec_b64 s[4:5], vcc
	s_cbranch_execz .LBB0_3588
	s_cmp_lg_u32 s86, 0x100
	s_cbranch_scc1 .Lxb_flat_8
	s_getreg_b32 s1, hwreg(HW_REG_XCC_ID, 0, 4)
	s_lshl_b32 s1, s1, 8
	s_add_u32 s12, s42, 0x600000
	s_addc_u32 s13, s43, 0
	s_add_u32 s12, s12, s1
	s_addc_u32 s13, s13, 0
	s_add_u32 s14, s42, 0x601000
	s_addc_u32 s15, s43, 0
	s_lshr_b32 s16, s86, 3
	v_mov_b32_e32 v2, 0
	v_mov_b32_e32 v3, 1
	v_mov_b32_e32 v7, v210
	global_atomic_add v4, v2, v3, s[12:13] sc0
	v_mul_lo_u32 v8, v7, s16
	s_mov_b32 s0, 0
	s_waitcnt vmcnt(0)
	v_add_u32_e32 v4, 1, v4
	v_cmp_eq_u32_e32 vcc, v4, v8
	s_cbranch_vccz .Lxb_nl_8
	buffer_wbl2 sc1
	s_waitcnt vmcnt(0)
	global_atomic_add v4, v2, v3, s[14:15] sc0
	v_lshlrev_b32_e32 v8, 3, v7
	s_waitcnt vmcnt(0)
	v_add_u32_e32 v4, 1, v4
	v_cmp_eq_u32_e32 vcc, v4, v8
	s_cbranch_vccz .Lxb_wt_8
	global_atomic_add v2, v3, s[14:15] offset:256
	s_branch .Lxb_lr_8

; #define SYNC(k) if (p.ph_lo <= (k) && (k) + 1 < p.ph_hi) { if ((k) == 0) grid.sync(); else gbar(bctr, bgen, gridDim.x); }
; DI void gbar(unsigned* ctr, unsigned& gen, unsigned G) {
;     ...
;         asm volatile("s_waitcnt vmcnt(0)" ::: "memory");
;     }
;     __syncthreads();
; __global__ void __launch_bounds__(NTHREADS) fwd_megakernel(Params p) {
;     ...
;     SYNC(9)
.Lxb_na_8:
	buffer_inv sc1
	s_waitcnt vmcnt(0)
.Lxb_dn_8:
	s_branch .Lxb_end_8

; #define SYNC(k) if (p.ph_lo <= (k) && (k) + 1 < p.ph_hi) { if ((k) == 0) grid.sync(); else gbar(bctr, bgen, gridDim.x); }
; DI void gbar(unsigned* ctr, unsigned& gen, unsigned G) {
;     asm volatile("s_waitcnt vmcnt(0)" ::: "memory");
;     __syncthreads();
;     gen += 1;
;     if (threadIdx.x == 0) {
;         __builtin_amdgcn_fence(__ATOMIC_RELEASE, "agent");
;         asm volatile("s_waitcnt vmcnt(0)" ::: "memory");
;         __hip_atomic_fetch_add(ctr, 1u, __ATOMIC_RELAXED, __HIP_MEMORY_SCOPE_AGENT);
;         while (__hip_atomic_load(ctr, __ATOMIC_RELAXED, __HIP_MEMORY_SCOPE_AGENT) < gen * G) __builtin_amdgcn_s_sleep(32);
;         __builtin_amdgcn_fence(__ATOMIC_ACQUIRE, "agent");
;         asm volatile("s_waitcnt vmcnt(0)" ::: "memory");
;     }
;     __syncthreads();
; }
; __global__ void __launch_bounds__(NTHREADS) fwd_megakernel(Params p) {
;     ...
;     SYNC(10)
.LBB0_3644:
	s_or_b64 exec, exec, s[8:9]
	v_cmp_gt_i32_e32 vcc, 11, v1
	v_cmp_lt_i32_e64 s[2:3], 11, v5
	s_and_b64 s[0:1], vcc, s[2:3]
	s_and_saveexec_b64 s[2:3], s[0:1]
	s_cbranch_execz .LBB0_3653
	s_waitcnt vmcnt(0)
	v_and_b32_e32 v2, 0x3ff, v0
	v_add_u32_e32 v210, 1, v210
	v_cmp_eq_u32_e32 vcc, 0, v2
	s_waitcnt vmcnt(0)
	s_barrier
	s_and_saveexec_b64 s[4:5], vcc
	s_cbranch_execz .LBB0_3652
	s_cmp_lg_u32 s86, 0x100
	s_cbranch_scc1 .Lxb_flat_9
	s_getreg_b32 s1, hwreg(HW_REG_XCC_ID, 0, 4)
	s_lshl_b32 s1, s1, 8
	s_add_u32 s12, s42, 0x600000
	s_addc_u32 s13, s43, 0
	s_add_u32 s12, s12, s1
	s_addc_u32 s13, s13, 0
	s_add_u32 s14, s42, 0x601000
	s_addc_u32 s15, s43, 0
	s_lshr_b32 s16, s86, 3
	v_mov_b32_e32 v2, 0
	v_mov_b32_e32 v3, 1
	v_mov_b32_e32 v7, v210
	global_atomic_add v4, v2, v3, s[12:13] sc0
	v_mul_lo_u32 v8, v7, s16
	s_mov_b32 s0, 0
	s_waitcnt vmcnt(0)
	v_add_u32_e32 v4, 1, v4
	v_cmp_eq_u32_e32 vcc, v4, v8
	s_cbranch_vccz .Lxb_nl_9
	buffer_wbl2 sc1
	s_waitcnt vmcnt(0)
	global_atomic_add v4, v2, v3, s[14:15] sc0
	v_lshlrev_b32_e32 v8, 3, v7
	s_waitcnt vmcnt(0)
	v_add_u32_e32 v4, 1, v4
	v_cmp_eq_u32_e32 vcc, v4, v8
	s_cbranch_vccz .Lxb_wt_9
	global_atomic_add v2, v3, s[14:15] offset:256
	s_branch .Lxb_lr_9

; DI void gbar(unsigned* ctr, unsigned& gen, unsigned G) {
;     asm volatile("s_waitcnt vmcnt(0)" ::: "memory");
;     __syncthreads();
;     gen += 1;
;     if (threadIdx.x == 0) {
;         __builtin_amdgcn_fence(__ATOMIC_RELEASE, "agent");
;         asm volatile("s_waitcnt vmcnt(0)" ::: "memory");
;         __hip_atomic_fetch_add(ctr, 1u, __ATOMIC_RELAXED, __HIP_MEMORY_SCOPE_AGENT);
;         while (__hip_atomic_load(ctr, __ATOMIC_RELAXED, __HIP_MEMORY_SCOPE_AGENT) < gen * G) __builtin_amdgcn_s_sleep(32);
;         __builtin_amdgcn_fence(__ATOMIC_ACQUIRE, "agent");
;         asm volatile("s_waitcnt vmcnt(0)" ::: "memory");
;     }
;     __syncthreads();
; }
.Lxb_na_9:
	buffer_inv sc1
	s_waitcnt vmcnt(0)
.Lxb_dn_9:
	s_branch .Lxb_end_9

; DI void gbar(unsigned* ctr, unsigned& gen, unsigned G) {
;     asm volatile("s_waitcnt vmcnt(0)" ::: "memory");
;     __syncthreads();
;     gen += 1;
;     if (threadIdx.x == 0) {
;         __builtin_amdgcn_fence(__ATOMIC_RELEASE, "agent");
;         asm volatile("s_waitcnt vmcnt(0)" ::: "memory");
;         __hip_atomic_fetch_add(ctr, 1u, __ATOMIC_RELAXED, __HIP_MEMORY_SCOPE_AGENT);
;         while (__hip_atomic_load(ctr, __ATOMIC_RELAXED, __HIP_MEMORY_SCOPE_AGENT) < gen * G) __builtin_amdgcn_s_sleep(32);
;         __builtin_amdgcn_fence(__ATOMIC_ACQUIRE, "agent");
;         asm volatile("s_waitcnt vmcnt(0)" ::: "memory");
;     }
;     __syncthreads();
; }
.LBB0_3696:
	s_or_b64 exec, exec, s[6:7]
	v_cmp_gt_i32_e32 vcc, 12, v1
	v_cmp_lt_i32_e64 s[2:3], 12, v5
	s_and_b64 s[0:1], vcc, s[2:3]
	s_and_saveexec_b64 s[2:3], s[0:1]
	s_cbranch_execz .LBB0_3705
	s_waitcnt vmcnt(0)
	v_and_b32_e32 v2, 0x3ff, v0
	v_add_u32_e32 v210, 1, v210
	v_cmp_eq_u32_e32 vcc, 0, v2
	s_waitcnt vmcnt(0) lgkmcnt(0)
	s_barrier
	s_and_saveexec_b64 s[4:5], vcc
	s_cbranch_execz .LBB0_3704
	s_cmp_lg_u32 s86, 0x100
	s_cbranch_scc1 .Lxb_flat_10
	s_getreg_b32 s1, hwreg(HW_REG_XCC_ID, 0, 4)
	s_lshl_b32 s1, s1, 8
	s_add_u32 s12, s42, 0x600000
	s_addc_u32 s13, s43, 0
	s_add_u32 s12, s12, s1
	s_addc_u32 s13, s13, 0
	s_add_u32 s14, s42, 0x601000
	s_addc_u32 s15, s43, 0
	s_lshr_b32 s16, s86, 3
	v_mov_b32_e32 v2, 0
	v_mov_b32_e32 v3, 1
	v_mov_b32_e32 v7, v210
	global_atomic_add v4, v2, v3, s[12:13] sc0
	v_mul_lo_u32 v8, v7, s16
	s_mov_b32 s0, 0
	s_waitcnt vmcnt(0)
	v_add_u32_e32 v4, 1, v4
	v_cmp_eq_u32_e32 vcc, v4, v8
	s_cbranch_vccz .Lxb_nl_10
	buffer_wbl2 sc1
	s_waitcnt vmcnt(0)
	global_atomic_add v4, v2, v3, s[14:15] sc0
	v_lshlrev_b32_e32 v8, 3, v7
	s_waitcnt vmcnt(0)
	v_add_u32_e32 v4, 1, v4
	v_cmp_eq_u32_e32 vcc, v4, v8
	s_cbranch_vccz .Lxb_wt_10
	global_atomic_add v2, v3, s[14:15] offset:256
	s_branch .Lxb_lr_10

; DI void gbar(unsigned* ctr, unsigned& gen, unsigned G) {
;     asm volatile("s_waitcnt vmcnt(0)" ::: "memory");
;     __syncthreads();
;     gen += 1;
;     if (threadIdx.x == 0) {
;         __builtin_amdgcn_fence(__ATOMIC_RELEASE, "agent");
;         asm volatile("s_waitcnt vmcnt(0)" ::: "memory");
;         __hip_atomic_fetch_add(ctr, 1u, __ATOMIC_RELAXED, __HIP_MEMORY_SCOPE_AGENT);
;         while (__hip_atomic_load(ctr, __ATOMIC_RELAXED, __HIP_MEMORY_SCOPE_AGENT) < gen * G) __builtin_amdgcn_s_sleep(32);
;         __builtin_amdgcn_fence(__ATOMIC_ACQUIRE, "agent");
;         asm volatile("s_waitcnt vmcnt(0)" ::: "memory");
;     }
;     __syncthreads();
; }
.Lxb_na_10:
	buffer_inv sc1
	s_waitcnt vmcnt(0)
.Lxb_dn_10:
	s_branch .Lxb_end_10

; DI void gbar(unsigned* ctr, unsigned& gen, unsigned G) {
;     asm volatile("s_waitcnt vmcnt(0)" ::: "memory");
;     __syncthreads();
;     gen += 1;
;     if (threadIdx.x == 0) {
;         __builtin_amdgcn_fence(__ATOMIC_RELEASE, "agent");
;         asm volatile("s_waitcnt vmcnt(0)" ::: "memory");
;         __hip_atomic_fetch_add(ctr, 1u, __ATOMIC_RELAXED, __HIP_MEMORY_SCOPE_AGENT);
;         while (__hip_atomic_load(ctr, __ATOMIC_RELAXED, __HIP_MEMORY_SCOPE_AGENT) < gen * G) __builtin_amdgcn_s_sleep(32);
;         __builtin_amdgcn_fence(__ATOMIC_ACQUIRE, "agent");
;         asm volatile("s_waitcnt vmcnt(0)" ::: "memory");
;     }
;     __syncthreads();
; }
.LBB0_3730:
	s_or_b64 exec, exec, s[4:5]
	v_cmp_gt_i32_e32 vcc, 13, v1
	v_cmp_lt_i32_e64 s[2:3], 13, v5
	s_and_b64 s[0:1], vcc, s[2:3]
	s_and_saveexec_b64 s[2:3], s[0:1]
	s_cbranch_execz .LBB0_3739
	s_waitcnt vmcnt(0)
	v_and_b32_e32 v2, 0x3ff, v0
	v_add_u32_e32 v210, 1, v210
	v_cmp_eq_u32_e32 vcc, 0, v2
	s_waitcnt vmcnt(0) lgkmcnt(0)
	s_barrier
	s_and_saveexec_b64 s[4:5], vcc
	s_cbranch_execz .LBB0_3738
	s_cmp_lg_u32 s86, 0x100
	s_cbranch_scc1 .Lxb_flat_11
	s_getreg_b32 s1, hwreg(HW_REG_XCC_ID, 0, 4)
	s_lshl_b32 s1, s1, 8
	s_add_u32 s12, s42, 0x600000
	s_addc_u32 s13, s43, 0
	s_add_u32 s12, s12, s1
	s_addc_u32 s13, s13, 0
	s_add_u32 s14, s42, 0x601000
	s_addc_u32 s15, s43, 0
	s_lshr_b32 s16, s86, 3
	v_mov_b32_e32 v2, 0
	v_mov_b32_e32 v3, 1
	v_mov_b32_e32 v7, v210
	global_atomic_add v4, v2, v3, s[12:13] sc0
	v_mul_lo_u32 v8, v7, s16
	s_mov_b32 s0, 0
	s_waitcnt vmcnt(0)
	v_add_u32_e32 v4, 1, v4
	v_cmp_eq_u32_e32 vcc, v4, v8
	s_cbranch_vccz .Lxb_nl_11
	buffer_wbl2 sc1
	s_waitcnt vmcnt(0)
	global_atomic_add v4, v2, v3, s[14:15] sc0
	v_lshlrev_b32_e32 v8, 3, v7
	s_waitcnt vmcnt(0)
	v_add_u32_e32 v4, 1, v4
	v_cmp_eq_u32_e32 vcc, v4, v8
	s_cbranch_vccz .Lxb_wt_11
	global_atomic_add v2, v3, s[14:15] offset:256
	s_branch .Lxb_lr_11

; DI void gbar(unsigned* ctr, unsigned& gen, unsigned G) {
;     asm volatile("s_waitcnt vmcnt(0)" ::: "memory");
;     __syncthreads();
;     gen += 1;
;     if (threadIdx.x == 0) {
;         __builtin_amdgcn_fence(__ATOMIC_RELEASE, "agent");
;         asm volatile("s_waitcnt vmcnt(0)" ::: "memory");
;         __hip_atomic_fetch_add(ctr, 1u, __ATOMIC_RELAXED, __HIP_MEMORY_SCOPE_AGENT);
;         while (__hip_atomic_load(ctr, __ATOMIC_RELAXED, __HIP_MEMORY_SCOPE_AGENT) < gen * G) __builtin_amdgcn_s_sleep(32);
;         __builtin_amdgcn_fence(__ATOMIC_ACQUIRE, "agent");
;         asm volatile("s_waitcnt vmcnt(0)" ::: "memory");
;     }
;     __syncthreads();
; }
.Lxb_na_11:
	buffer_inv sc1
	s_waitcnt vmcnt(0)
.Lxb_dn_11:
	s_branch .Lxb_end_11

; DI void gbar(unsigned* ctr, unsigned& gen, unsigned G) {
;     asm volatile("s_waitcnt vmcnt(0)" ::: "memory");
;     __syncthreads();
;     gen += 1;
;     if (threadIdx.x == 0) {
;         __builtin_amdgcn_fence(__ATOMIC_RELEASE, "agent");
;         asm volatile("s_waitcnt vmcnt(0)" ::: "memory");
;         __hip_atomic_fetch_add(ctr, 1u, __ATOMIC_RELAXED, __HIP_MEMORY_SCOPE_AGENT);
;         while (__hip_atomic_load(ctr, __ATOMIC_RELAXED, __HIP_MEMORY_SCOPE_AGENT) < gen * G) __builtin_amdgcn_s_sleep(32);
;         __builtin_amdgcn_fence(__ATOMIC_ACQUIRE, "agent");
;         asm volatile("s_waitcnt vmcnt(0)" ::: "memory");
;     }
;     __syncthreads();
; }
.LBB0_3782:
	s_or_b64 exec, exec, s[6:7]
	v_cmp_gt_i32_e32 vcc, 14, v1
	v_cmp_lt_i32_e64 s[2:3], 14, v5
	s_and_b64 s[0:1], vcc, s[2:3]
	s_and_saveexec_b64 s[2:3], s[0:1]
	s_cbranch_execz .LBB0_3791
	s_waitcnt vmcnt(0)
	v_and_b32_e32 v2, 0x3ff, v0
	v_cmp_eq_u32_e32 vcc, 0, v2
	s_waitcnt vmcnt(0) lgkmcnt(0)
	s_barrier
	s_and_saveexec_b64 s[4:5], vcc
	s_cbranch_execz .LBB0_3790
	s_cmp_lg_u32 s86, 0x100
	s_cbranch_scc1 .Lxb_flat_12
	s_getreg_b32 s1, hwreg(HW_REG_XCC_ID, 0, 4)
	s_lshl_b32 s1, s1, 8
	s_add_u32 s12, s42, 0x600000
	s_addc_u32 s13, s43, 0
	s_add_u32 s12, s12, s1
	s_addc_u32 s13, s13, 0
	s_add_u32 s14, s42, 0x601000
	s_addc_u32 s15, s43, 0
	s_lshr_b32 s16, s86, 3
	v_mov_b32_e32 v2, 0
	v_mov_b32_e32 v3, 1
	v_add_u32_e32 v7, 1, v210
	global_atomic_add v4, v2, v3, s[12:13] sc0
	v_mul_lo_u32 v8, v7, s16
	s_mov_b32 s0, 0
	s_waitcnt vmcnt(0)
	v_add_u32_e32 v4, 1, v4
	v_cmp_eq_u32_e32 vcc, v4, v8
	s_cbranch_vccz .Lxb_nl_12
	buffer_wbl2 sc1
	s_waitcnt vmcnt(0)
	global_atomic_add v4, v2, v3, s[14:15] sc0
	v_lshlrev_b32_e32 v8, 3, v7
	s_waitcnt vmcnt(0)
	v_add_u32_e32 v4, 1, v4
	v_cmp_eq_u32_e32 vcc, v4, v8
	s_cbranch_vccz .Lxb_wt_12
	global_atomic_add v2, v3, s[14:15] offset:256
	s_branch .Lxb_lr_12

; DI void gbar(unsigned* ctr, unsigned& gen, unsigned G) {
;     asm volatile("s_waitcnt vmcnt(0)" ::: "memory");
;     __syncthreads();
;     gen += 1;
;     if (threadIdx.x == 0) {
;         __builtin_amdgcn_fence(__ATOMIC_RELEASE, "agent");
;         asm volatile("s_waitcnt vmcnt(0)" ::: "memory");
;         __hip_atomic_fetch_add(ctr, 1u, __ATOMIC_RELAXED, __HIP_MEMORY_SCOPE_AGENT);
;         while (__hip_atomic_load(ctr, __ATOMIC_RELAXED, __HIP_MEMORY_SCOPE_AGENT) < gen * G) __builtin_amdgcn_s_sleep(32);
;         __builtin_amdgcn_fence(__ATOMIC_ACQUIRE, "agent");
;         asm volatile("s_waitcnt vmcnt(0)" ::: "memory");
;     }
;     __syncthreads();
; }
.Lxb_na_12:
	buffer_inv sc1
	s_waitcnt vmcnt(0)
.Lxb_dn_12:
	s_branch .Lxb_end_12
